# split-K handoff: one wbl2+atomic(8) and one spin+inv per workgroup (wave 0) with a workgroup barrier, instead of per-wave fences
# speedup vs baseline: 1.0110x; 1.0109x over previous
.Lal_e0_q:
	v_readlane_b32 s98, v246, 0
	v_readlane_b32 s99, v246, 1
	s_cmp_eq_u32 s99, 0
	s_cbranch_scc1 .Lm2_epi
	s_and_b32 s100, s2, 0x7f
	s_lshl_b32 s100, s100, 18
	s_add_u32 s100, s100, 0x29800000
	s_add_u32 s100, s46, s100
	s_addc_u32 s101, s47, 0
	v_lshlrev_b32_e32 v186, 4, v182
	s_cmp_eq_u32 s99, 1
	s_cbranch_scc1 .Lm2_put_partial
	s_cmpk_gt_u32 s42, 0x3f
	s_cbranch_scc1 .Lm2_spin_done
	s_and_b32 s6, s2, 0x7f
	s_lshl_b32 s6, s6, 6
	s_add_u32 s6, s6, 0x2970a000
	s_add_u32 s6, s46, s6
	s_addc_u32 s7, s47, 0
	v_mov_b32_e32 v187, 0
	s_mov_b32 s99, 0

.Lm2_spin_done:
	s_barrier
	global_load_dwordx4 v[210:213], v186, s[100:101]
	s_add_u32 s100, s100, 0x2000
	s_addc_u32 s101, s101, 0
	global_load_dwordx4 v[214:217], v186, s[100:101]
	s_add_u32 s100, s100, 0x2000
	s_addc_u32 s101, s101, 0
	global_load_dwordx4 v[218:221], v186, s[100:101]
	s_add_u32 s100, s100, 0x2000
	s_addc_u32 s101, s101, 0
	global_load_dwordx4 v[222:225], v186, s[100:101]
	s_add_u32 s100, s100, 0x2000
	s_addc_u32 s101, s101, 0
	global_load_dwordx4 v[226:229], v186, s[100:101]
	s_add_u32 s100, s100, 0x2000
	s_addc_u32 s101, s101, 0
	global_load_dwordx4 v[230:233], v186, s[100:101]
	s_add_u32 s100, s100, 0x2000
	s_addc_u32 s101, s101, 0
	global_load_dwordx4 v[234:237], v186, s[100:101]
	s_add_u32 s100, s100, 0x2000
	s_addc_u32 s101, s101, 0
	global_load_dwordx4 v[238:241], v186, s[100:101]
	s_add_u32 s100, s100, 0x2000
	s_addc_u32 s101, s101, 0
	s_waitcnt vmcnt(7)
	v_pk_add_f32 v[140:141], v[140:141], v[210:211]
	v_pk_add_f32 v[142:143], v[142:143], v[212:213]
	s_waitcnt vmcnt(6)
	v_pk_add_f32 v[128:129], v[128:129], v[214:215]
	v_pk_add_f32 v[130:131], v[130:131], v[216:217]
	s_waitcnt vmcnt(5)
	v_pk_add_f32 v[116:117], v[116:117], v[218:219]
	v_pk_add_f32 v[118:119], v[118:119], v[220:221]
	s_waitcnt vmcnt(4)
	v_pk_add_f32 v[108:109], v[108:109], v[222:223]
	v_pk_add_f32 v[110:111], v[110:111], v[224:225]
	s_waitcnt vmcnt(3)
	v_pk_add_f32 v[112:113], v[112:113], v[226:227]
	v_pk_add_f32 v[114:115], v[114:115], v[228:229]
	s_waitcnt vmcnt(2)
	v_pk_add_f32 v[104:105], v[104:105], v[230:231]
	v_pk_add_f32 v[106:107], v[106:107], v[232:233]
	s_waitcnt vmcnt(1)
	v_pk_add_f32 v[100:101], v[100:101], v[234:235]
	v_pk_add_f32 v[102:103], v[102:103], v[236:237]
	s_waitcnt vmcnt(0)
	v_pk_add_f32 v[92:93], v[92:93], v[238:239]
	v_pk_add_f32 v[94:95], v[94:95], v[240:241]
	global_load_dwordx4 v[210:213], v186, s[100:101]
	s_add_u32 s100, s100, 0x2000
	s_addc_u32 s101, s101, 0
	global_load_dwordx4 v[214:217], v186, s[100:101]
	s_add_u32 s100, s100, 0x2000
	s_addc_u32 s101, s101, 0
	global_load_dwordx4 v[218:221], v186, s[100:101]
	s_add_u32 s100, s100, 0x2000
	s_addc_u32 s101, s101, 0
	global_load_dwordx4 v[222:225], v186, s[100:101]
	s_add_u32 s100, s100, 0x2000
	s_addc_u32 s101, s101, 0
	global_load_dwordx4 v[226:229], v186, s[100:101]
	s_add_u32 s100, s100, 0x2000
	s_addc_u32 s101, s101, 0
	global_load_dwordx4 v[230:233], v186, s[100:101]
	s_add_u32 s100, s100, 0x2000
	s_addc_u32 s101, s101, 0
	global_load_dwordx4 v[234:237], v186, s[100:101]
	s_add_u32 s100, s100, 0x2000
	s_addc_u32 s101, s101, 0
	global_load_dwordx4 v[238:241], v186, s[100:101]
	s_add_u32 s100, s100, 0x2000
	s_addc_u32 s101, s101, 0
	s_waitcnt vmcnt(7)
	v_pk_add_f32 v[96:97], v[96:97], v[210:211]
	v_pk_add_f32 v[98:99], v[98:99], v[212:213]
	s_waitcnt vmcnt(6)
	v_pk_add_f32 v[88:89], v[88:89], v[214:215]
	v_pk_add_f32 v[90:91], v[90:91], v[216:217]
	s_waitcnt vmcnt(5)
	v_pk_add_f32 v[84:85], v[84:85], v[218:219]
	v_pk_add_f32 v[86:87], v[86:87], v[220:221]
	s_waitcnt vmcnt(4)
	v_pk_add_f32 v[76:77], v[76:77], v[222:223]
	v_pk_add_f32 v[78:79], v[78:79], v[224:225]
	s_waitcnt vmcnt(3)
	v_pk_add_f32 v[80:81], v[80:81], v[226:227]
	v_pk_add_f32 v[82:83], v[82:83], v[228:229]
	s_waitcnt vmcnt(2)
	v_pk_add_f32 v[72:73], v[72:73], v[230:231]
	v_pk_add_f32 v[74:75], v[74:75], v[232:233]
	s_waitcnt vmcnt(1)
	v_pk_add_f32 v[68:69], v[68:69], v[234:235]
	v_pk_add_f32 v[70:71], v[70:71], v[236:237]
	s_waitcnt vmcnt(0)
	v_pk_add_f32 v[64:65], v[64:65], v[238:239]
	v_pk_add_f32 v[66:67], v[66:67], v[240:241]
	global_load_dwordx4 v[210:213], v186, s[100:101]
	s_add_u32 s100, s100, 0x2000
	s_addc_u32 s101, s101, 0
	global_load_dwordx4 v[214:217], v186, s[100:101]
	s_add_u32 s100, s100, 0x2000
	s_addc_u32 s101, s101, 0
	global_load_dwordx4 v[218:221], v186, s[100:101]
	s_add_u32 s100, s100, 0x2000
	s_addc_u32 s101, s101, 0
	global_load_dwordx4 v[222:225], v186, s[100:101]
	s_add_u32 s100, s100, 0x2000
	s_addc_u32 s101, s101, 0
	global_load_dwordx4 v[226:229], v186, s[100:101]
	s_add_u32 s100, s100, 0x2000
	s_addc_u32 s101, s101, 0
	global_load_dwordx4 v[230:233], v186, s[100:101]
	s_add_u32 s100, s100, 0x2000
	s_addc_u32 s101, s101, 0
	global_load_dwordx4 v[234:237], v186, s[100:101]
	s_add_u32 s100, s100, 0x2000
	s_addc_u32 s101, s101, 0
	global_load_dwordx4 v[238:241], v186, s[100:101]
	s_add_u32 s100, s100, 0x2000
	s_addc_u32 s101, s101, 0
	s_waitcnt vmcnt(7)
	v_pk_add_f32 v[60:61], v[60:61], v[210:211]
	v_pk_add_f32 v[62:63], v[62:63], v[212:213]
	s_waitcnt vmcnt(6)
	v_pk_add_f32 v[56:57], v[56:57], v[214:215]
	v_pk_add_f32 v[58:59], v[58:59], v[216:217]
	s_waitcnt vmcnt(5)
	v_pk_add_f32 v[52:53], v[52:53], v[218:219]
	v_pk_add_f32 v[54:55], v[54:55], v[220:221]
	s_waitcnt vmcnt(4)
	v_pk_add_f32 v[44:45], v[44:45], v[222:223]
	v_pk_add_f32 v[46:47], v[46:47], v[224:225]
	s_waitcnt vmcnt(3)
	v_pk_add_f32 v[48:49], v[48:49], v[226:227]
	v_pk_add_f32 v[50:51], v[50:51], v[228:229]
	s_waitcnt vmcnt(2)
	v_pk_add_f32 v[40:41], v[40:41], v[230:231]
	v_pk_add_f32 v[42:43], v[42:43], v[232:233]
	s_waitcnt vmcnt(1)
	v_pk_add_f32 v[36:37], v[36:37], v[234:235]
	v_pk_add_f32 v[38:39], v[38:39], v[236:237]
	s_waitcnt vmcnt(0)
	v_pk_add_f32 v[28:29], v[28:29], v[238:239]
	v_pk_add_f32 v[30:31], v[30:31], v[240:241]
	global_load_dwordx4 v[210:213], v186, s[100:101]
	s_add_u32 s100, s100, 0x2000
	s_addc_u32 s101, s101, 0
	global_load_dwordx4 v[214:217], v186, s[100:101]
	s_add_u32 s100, s100, 0x2000
	s_addc_u32 s101, s101, 0
	global_load_dwordx4 v[218:221], v186, s[100:101]
	s_add_u32 s100, s100, 0x2000
	s_addc_u32 s101, s101, 0
	global_load_dwordx4 v[222:225], v186, s[100:101]
	s_add_u32 s100, s100, 0x2000
	s_addc_u32 s101, s101, 0
	global_load_dwordx4 v[226:229], v186, s[100:101]
	s_add_u32 s100, s100, 0x2000
	s_addc_u32 s101, s101, 0
	global_load_dwordx4 v[230:233], v186, s[100:101]
	s_add_u32 s100, s100, 0x2000
	s_addc_u32 s101, s101, 0
	global_load_dwordx4 v[234:237], v186, s[100:101]
	s_add_u32 s100, s100, 0x2000
	s_addc_u32 s101, s101, 0
	global_load_dwordx4 v[238:241], v186, s[100:101]
	s_add_u32 s100, s100, 0x2000
	s_addc_u32 s101, s101, 0
	s_waitcnt vmcnt(7)
	v_pk_add_f32 v[32:33], v[32:33], v[210:211]
	v_pk_add_f32 v[34:35], v[34:35], v[212:213]
	s_waitcnt vmcnt(6)
	v_pk_add_f32 v[24:25], v[24:25], v[214:215]
	v_pk_add_f32 v[26:27], v[26:27], v[216:217]
	s_waitcnt vmcnt(5)
	v_pk_add_f32 v[20:21], v[20:21], v[218:219]
	v_pk_add_f32 v[22:23], v[22:23], v[220:221]
	s_waitcnt vmcnt(4)
	v_pk_add_f32 v[12:13], v[12:13], v[222:223]
	v_pk_add_f32 v[14:15], v[14:15], v[224:225]
	s_waitcnt vmcnt(3)
	v_pk_add_f32 v[16:17], v[16:17], v[226:227]
	v_pk_add_f32 v[18:19], v[18:19], v[228:229]
	s_waitcnt vmcnt(2)
	v_pk_add_f32 v[8:9], v[8:9], v[230:231]
	v_pk_add_f32 v[10:11], v[10:11], v[232:233]
	s_waitcnt vmcnt(1)
	v_pk_add_f32 v[4:5], v[4:5], v[234:235]
	v_pk_add_f32 v[6:7], v[6:7], v[236:237]
	s_waitcnt vmcnt(0)
	v_pk_add_f32 v[0:1], v[0:1], v[238:239]
	v_pk_add_f32 v[2:3], v[2:3], v[240:241]
	s_branch .Lm2_epi
.Lm2_put_partial:
	s_nop 7
	s_nop 7
	global_store_dwordx4 v186, v[140:143], s[100:101]
	s_add_u32 s100, s100, 0x2000
	s_addc_u32 s101, s101, 0
	global_store_dwordx4 v186, v[128:131], s[100:101]
	s_add_u32 s100, s100, 0x2000
	s_addc_u32 s101, s101, 0
	global_store_dwordx4 v186, v[116:119], s[100:101]
	s_add_u32 s100, s100, 0x2000
	s_addc_u32 s101, s101, 0
	global_store_dwordx4 v186, v[108:111], s[100:101]
	s_add_u32 s100, s100, 0x2000
	s_addc_u32 s101, s101, 0
	global_store_dwordx4 v186, v[112:115], s[100:101]
	s_add_u32 s100, s100, 0x2000
	s_addc_u32 s101, s101, 0
	global_store_dwordx4 v186, v[104:107], s[100:101]
	s_add_u32 s100, s100, 0x2000
	s_addc_u32 s101, s101, 0
	global_store_dwordx4 v186, v[100:103], s[100:101]
	s_add_u32 s100, s100, 0x2000
	s_addc_u32 s101, s101, 0
	global_store_dwordx4 v186, v[92:95], s[100:101]
	s_add_u32 s100, s100, 0x2000
	s_addc_u32 s101, s101, 0
	global_store_dwordx4 v186, v[96:99], s[100:101]
	s_add_u32 s100, s100, 0x2000
	s_addc_u32 s101, s101, 0
	global_store_dwordx4 v186, v[88:91], s[100:101]
	s_add_u32 s100, s100, 0x2000
	s_addc_u32 s101, s101, 0
	global_store_dwordx4 v186, v[84:87], s[100:101]
	s_add_u32 s100, s100, 0x2000
	s_addc_u32 s101, s101, 0
	global_store_dwordx4 v186, v[76:79], s[100:101]
	s_add_u32 s100, s100, 0x2000
	s_addc_u32 s101, s101, 0
	global_store_dwordx4 v186, v[80:83], s[100:101]
	s_add_u32 s100, s100, 0x2000
	s_addc_u32 s101, s101, 0
	global_store_dwordx4 v186, v[72:75], s[100:101]
	s_add_u32 s100, s100, 0x2000
	s_addc_u32 s101, s101, 0
	global_store_dwordx4 v186, v[68:71], s[100:101]
	s_add_u32 s100, s100, 0x2000
	s_addc_u32 s101, s101, 0
	global_store_dwordx4 v186, v[64:67], s[100:101]
	s_add_u32 s100, s100, 0x2000
	s_addc_u32 s101, s101, 0
	global_store_dwordx4 v186, v[60:63], s[100:101]
	s_add_u32 s100, s100, 0x2000
	s_addc_u32 s101, s101, 0
	global_store_dwordx4 v186, v[56:59], s[100:101]
	s_add_u32 s100, s100, 0x2000
	s_addc_u32 s101, s101, 0
	global_store_dwordx4 v186, v[52:55], s[100:101]
	s_add_u32 s100, s100, 0x2000
	s_addc_u32 s101, s101, 0
	global_store_dwordx4 v186, v[44:47], s[100:101]
	s_add_u32 s100, s100, 0x2000
	s_addc_u32 s101, s101, 0
	global_store_dwordx4 v186, v[48:51], s[100:101]
	s_add_u32 s100, s100, 0x2000
	s_addc_u32 s101, s101, 0
	global_store_dwordx4 v186, v[40:43], s[100:101]
	s_add_u32 s100, s100, 0x2000
	s_addc_u32 s101, s101, 0
	global_store_dwordx4 v186, v[36:39], s[100:101]
	s_add_u32 s100, s100, 0x2000
	s_addc_u32 s101, s101, 0
	global_store_dwordx4 v186, v[28:31], s[100:101]
	s_add_u32 s100, s100, 0x2000
	s_addc_u32 s101, s101, 0
	global_store_dwordx4 v186, v[32:35], s[100:101]
	s_add_u32 s100, s100, 0x2000
	s_addc_u32 s101, s101, 0
	global_store_dwordx4 v186, v[24:27], s[100:101]
	s_add_u32 s100, s100, 0x2000
	s_addc_u32 s101, s101, 0
	global_store_dwordx4 v186, v[20:23], s[100:101]
	s_add_u32 s100, s100, 0x2000
	s_addc_u32 s101, s101, 0
	global_store_dwordx4 v186, v[12:15], s[100:101]
	s_add_u32 s100, s100, 0x2000
	s_addc_u32 s101, s101, 0
	global_store_dwordx4 v186, v[16:19], s[100:101]
	s_add_u32 s100, s100, 0x2000
	s_addc_u32 s101, s101, 0
	global_store_dwordx4 v186, v[8:11], s[100:101]
	s_add_u32 s100, s100, 0x2000
	s_addc_u32 s101, s101, 0
	global_store_dwordx4 v186, v[4:7], s[100:101]
	s_add_u32 s100, s100, 0x2000
	s_addc_u32 s101, s101, 0
	global_store_dwordx4 v186, v[0:3], s[100:101]
	s_add_u32 s100, s100, 0x2000
	s_addc_u32 s101, s101, 0
	s_waitcnt vmcnt(0)
	s_barrier
	s_cmpk_gt_u32 s42, 0x3f
	s_cbranch_scc1 .Lm2_epi_tail
	buffer_wbl2 sc1
	s_waitcnt vmcnt(0)
	s_and_b32 s6, s2, 0x7f
	s_lshl_b32 s6, s6, 6
	s_add_u32 s6, s6, 0x2970a000
	s_add_u32 s6, s46, s6
	s_addc_u32 s7, s47, 0
	v_mov_b32_e32 v187, 0
	v_mov_b32_e32 v188, 8
	s_mov_b64 exec, 1
	global_atomic_add v187, v188, s[6:7]
	s_mov_b64 exec, -1
	s_branch .Lm2_epi_tail
